# attention: all K-fragment reloads issued after the last QK MFMA (single LDS burst)
# speedup vs baseline: 1.0060x; 1.0060x over previous
.LBB0_790:
	s_waitcnt lgkmcnt(3)
	v_mfma_f32_16x16x32_bf16 v[152:155], v[144:147], v[72:75], v[228:231]
	s_waitcnt lgkmcnt(2)
	v_mfma_f32_16x16x32_bf16 v[192:195], v[148:151], v[76:79], v[152:155]
	v_mfma_f32_16x16x32_bf16 v[152:155], v[144:147], v[84:87], v[232:235]
	v_mfma_f32_16x16x32_bf16 v[180:183], v[148:151], v[88:91], v[152:155]
	s_mov_b32 s6, s53
	s_add_i32 s53, s53, 1
	s_cmp_ge_u32 s53, s52
	v_mfma_f32_16x16x32_bf16 v[152:155], v[144:147], v[100:103], v[248:251]
	s_cselect_b64 s[34:35], -1, 0
	s_cmp_lt_u32 s53, s52
	s_cselect_b32 s6, s53, s6
	v_mfma_f32_16x16x32_bf16 v[144:147], v[144:147], v[108:111], v[220:223]
	v_lshl_or_b32 v37, s6, 5, v201
	v_mad_u32_u24 v38, v37, s3, v32
	v_mfma_f32_16x16x32_bf16 v[156:159], v[148:151], v[104:107], v[152:155]
	v_mfma_f32_16x16x32_bf16 v[152:155], v[148:151], v[112:115], v[144:147]
	s_waitcnt lgkmcnt(1)
	v_mfma_f32_16x16x32_bf16 v[144:147], v[140:143], v[72:75], v[228:231]
	s_waitcnt lgkmcnt(0)
	v_mfma_f32_16x16x32_bf16 v[196:199], v[136:139], v[76:79], v[144:147]
	s_nop 0
	v_mfma_f32_16x16x32_bf16 v[144:147], v[140:143], v[84:87], v[232:235]
	v_mfma_f32_16x16x32_bf16 v[188:191], v[136:139], v[88:91], v[144:147]
	v_mfma_f32_16x16x32_bf16 v[144:147], v[140:143], v[100:103], v[248:251]
	v_mfma_f32_16x16x32_bf16 v[140:143], v[140:143], v[108:111], v[220:223]
	v_mfma_f32_16x16x32_bf16 v[184:187], v[136:139], v[104:107], v[144:147]
	v_mfma_f32_16x16x32_bf16 v[172:175], v[136:139], v[112:115], v[140:143]
	s_nop 4
	ds_read_b128 v[144:147], v38
	ds_read_b128 v[148:151], v38 offset:64
	ds_read_b128 v[140:143], v38 offset:2304
	ds_read_b128 v[136:139], v38 offset:2368
	ds_read_b64_tr_b16 v[168:169], v35
	ds_read_b64_tr_b16 v[170:171], v35 offset:2560
	ds_read_b64_tr_b16 v[160:161], v35 offset:32
	ds_read_b64_tr_b16 v[162:163], v35 offset:2592
	ds_read_b64_tr_b16 v[176:177], v35 offset:64
	ds_read_b64_tr_b16 v[178:179], v35 offset:2624
	ds_read_b64_tr_b16 v[164:165], v35 offset:96
	ds_read_b64_tr_b16 v[166:167], v35 offset:2656
	s_andn2_b64 vcc, exec, s[86:87]
	s_cbranch_vccnz .LBB0_792
